# attention: one long differential item per CU (workgroups with bit 4 of j clear) and two MLA items on the CU-mate, assigned statically; prompt items by ticket
# baseline (speedup 1.0000x reference)
.Lhw_bar_scope:
	s_and_b32 s9, s82, 7
	s_lshl_b32 s9, s9, 4
	s_add_i32 s9, s9, s83
	s_add_i32 s9, s9, 1
	s_cmpk_lt_u32 s83, 16
	s_cselect_b32 s9, s9, 0
	v_writelane_b32 v246, s9, 45
	s_and_b32 s9, s83, 15
	s_lshr_b32 s8, s83, 5
	s_lshl_b32 s8, s8, 4
	s_or_b32 s9, s9, s8
	s_and_b32 s8, s82, 7
	s_lshl_b32 s8, s8, 5
	s_add_i32 s9, s9, s8
	s_lshl_b32 s8, s9, 1
	s_addk_i32 s8, 0x101
	s_add_i32 s2, s8, 1
	s_add_i32 s9, s9, 1
	s_bitcmp1_b32 s83, 4
	s_cselect_b32 s9, s8, s9
	s_cselect_b32 s2, s2, 0
	v_writelane_b32 v246, s9, 46
	v_writelane_b32 v246, s2, 47
	v_readlane_b32 s2, v246, 26
	s_and_b32 s9, s88, 1
	s_lshl_b32 s8, s9, 8
	s_xor_b32 s9, s9, 1
	s_lshl_b32 s9, s9, 6
	s_or_b32 s8, s8, s9
	s_or_b32 s8, s8, 0xe1e
	s_lshr_b32 s8, s8, s2
	v_readlane_b32 s6, v246, 41
	s_and_b32 s8, s8, 1
	s_and_b32 s8, s8, s6
	v_writelane_b32 v246, s8, 42
	s_waitcnt vmcnt(0)
	s_barrier
	v_mov_b32 v0, v194
	s_nop 0
	v_cmp_eq_u32_e32 vcc, 0, v0
	s_and_saveexec_b64 s[0:1], vcc
	s_cbranch_execz .LBB0_108
	s_waitcnt vmcnt(0) expcnt(0) lgkmcnt(0)
	ds_read_b32 v3, v1
	ds_read_b32 v0, v1 offset:4
	s_waitcnt lgkmcnt(1)
	v_cmp_ne_u32_e32 vcc, 0, v3
	s_cbranch_vccnz .LBB0_71
	s_mov_b32 s2, 1
	s_branch .LBB0_54

.LBB0_427:
	s_barrier
	v_readlane_b32 s6, v246, 46
	s_cmp_eq_u32 s6, 0
	s_cbranch_scc1 .Lhw_attn_fetch
	v_readlane_b32 s2, v246, 47
	s_add_i32 s6, s6, -1
	s_nop 0
	v_writelane_b32 v246, s2, 46
	s_mov_b32 s2, 0
	s_nop 0
	v_writelane_b32 v246, s2, 47
	s_branch .Lhw_attn_have_item
.Lhw_attn_fetch:
	s_and_saveexec_b64 s[10:11], s[40:41]
	s_cbranch_execz .LBB0_431
	s_mov_b64 s[14:15], exec
	v_mbcnt_lo_u32_b32 v0, s14, 0
	v_mbcnt_hi_u32_b32 v0, s15, v0
	v_cmp_eq_u32_e32 vcc, 0, v0
	s_and_saveexec_b64 s[12:13], vcc
	s_cbranch_execz .LBB0_430
	s_bcnt1_i32_b64 s2, s[14:15]
	v_mov_b32_e32 v2, s2
	global_atomic_add v2, v1, v2, s[54:55] sc0

.LBB0_431:
	s_or_b64 exec, exec, s[10:11]
	s_waitcnt lgkmcnt(0)
	s_barrier
	ds_read_b32 v0, v204 offset:49152
	s_movk_i32 s2, 0x17f
	s_mov_b64 s[10:11], -1
	s_waitcnt lgkmcnt(0)
	v_cmp_lt_i32_e32 vcc, s2, v0
	v_readfirstlane_b32 s6, v0
	s_cbranch_vccnz .LBB0_426
	s_addk_i32 s6, 0x300
.Lhw_attn_have_item:
	s_cmpk_gt_i32 s6, 0xff
	s_mov_b64 s[14:15], -1
	s_cbranch_scc0 .LBB0_441
	s_cmpk_gt_u32 s6, 0x2ff
	s_mov_b64 s[12:13], -1
	s_cbranch_scc0 .LBB0_439
	s_cmpk_gt_u32 s6, 0x37f
	s_mov_b64 s[10:11], -1
	s_cbranch_scc0 .LBB0_436
	s_add_i32 s2, s6, 0xfffffc80
	s_lshr_b32 s24, s2, 4
	s_bfe_u32 s2, s6, 0x30001
	s_mov_b64 s[10:11], 0
